# GU2 too: rowss loads issued at the top of each unit; W_in and GU2 epilogues have no load and no wait
# speedup vs baseline: 1.0033x; 1.0019x over previous
;     __host__ __device__ bool next(int i, Unit& u) const {
;         const long L = (long)i * G + c; if (L >= nwg) return false;
;         int wgid = (int)L; { const int q = nwg / NXCD, r = nwg % NXCD, xcd = wgid % NXCD, off = wgid / NXCD; wgid = (xcd < r ? xcd * (q + 1) : r * (q + 1) + (xcd - r) * q) + off; }
;         const int nig = WGM * nN, gid = wgid / nig, fm = gid * WGM, gsz = (nM - fm) < WGM ? (nM - fm) : WGM;
;         u.pm = fm + ((wgid % nig) % gsz); u.pn = (wgid % nig) / gsz; return true;
; template <class Epi, class Sched, bool ALIGN_EPI = false, bool SP2 = false>
; __device__ __forceinline__ void gemm_phase(PG8_LAS unsigned char* lds, const Gemm g, const Sched& S, const Epi& E) {
;     ...
;     for (;;) {
;         const bool has_next = S.next(ui + 1, nxt);
;         const char* nA = has_next ? (const char*)g.A + (size_t)nxt.pm * tstep : cA; const char* nB = has_next ? (const char*)g.Bt + (size_t)nxt.pn * tstep : cB;
.LBB0_1100:
	v_lshl_add_u32 v238, s20, 8, v152
	v_ashrrev_i32_e32 v239, 31, v238
	v_lshl_add_u64 v[238:239], v[238:239], 2, s[0:1]
	global_load_dword v237, v[238:239], off
	global_load_dword v230, v[238:239], off offset:64
	global_load_dword v231, v[238:239], off offset:128
	global_load_dword v232, v[238:239], off offset:192
	global_load_dword v233, v[238:239], off offset:512
	global_load_dword v234, v[238:239], off offset:576
	global_load_dword v235, v[238:239], off offset:640
	global_load_dword v236, v[238:239], off offset:704
	s_add_i32 s40, s40, 1
	s_mul_i32 s2, s40, s41
	s_mul_hi_u32 s3, s40, s44
	s_add_i32 s3, s3, s2
	s_mul_i32 s2, s40, s44
	s_add_u32 s16, s2, s33
	s_addc_u32 s17, s3, s35
	v_cmp_gt_i64_e32 vcc, s[16:17], v[142:143]
	v_cmp_lt_i64_e64 s[2:3], s[16:17], v[140:141]
	s_cbranch_vccnz .LBB0_1102
	s_ashr_i32 s12, s16, 31
	s_lshr_b32 s12, s12, 29
	s_add_i32 s12, s16, s12
	s_ashr_i32 s13, s12, 3
	s_and_b32 s12, s12, -8
	s_sub_i32 s12, s16, s12
	s_cmp_lt_i32 s12, 0
	s_cselect_b32 s14, s36, 0xb0
	s_mul_i32 s12, s12, s14
	s_add_i32 s12, s12, s13
	s_mul_hi_i32 s13, s12, 0x2e8ba2e9
	s_lshr_b32 s14, s13, 31
	s_ashr_i32 s13, s13, 5
	s_add_i32 s13, s13, s14
	s_lshl_b32 s14, s13, 3
	s_sub_i32 s15, 64, s14
	s_min_i32 s15, s15, 8
	s_abs_i32 s16, s15
	v_cvt_f32_u32_e32 v0, s16
	s_sub_i32 s18, 0, s16
	s_mulk_i32 s13, 0xb0
	s_sub_i32 s13, s12, s13
	v_rcp_iflag_f32_e32 v0, v0
	s_abs_i32 s12, s13
	s_xor_b32 s17, s13, s15
	s_ashr_i32 s17, s17, 31
	v_mul_f32_e32 v0, 0x4f7ffffe, v0
	v_cvt_u32_f32_e32 v0, v0
	s_nop 0
	v_readfirstlane_b32 s19, v0
	s_mul_i32 s18, s18, s19
	s_mul_hi_u32 s18, s19, s18
	s_add_i32 s19, s19, s18
	s_mul_hi_u32 s18, s12, s19
	s_mul_i32 s19, s18, s16
	s_sub_i32 s12, s12, s19
	s_add_i32 s26, s18, 1
	s_sub_i32 s19, s12, s16
	s_cmp_ge_u32 s12, s16
	s_cselect_b32 s18, s26, s18
	s_cselect_b32 s12, s19, s12
	s_add_i32 s19, s18, 1
	s_cmp_ge_u32 s12, s16
	s_cselect_b32 s12, s19, s18
	s_xor_b32 s12, s12, s17
	s_sub_i32 s12, s12, s17
	s_mul_i32 s15, s12, s15
	s_sub_i32 s13, s13, s15
	s_add_i32 s14, s14, s13

; __device__ __forceinline__ unsigned cvt_pk_bf16(float lo, float hi) { f32x2_t v = {lo, hi}; bf16x2_t b = __builtin_convertvector(v, bf16x2_t); return __builtin_bit_cast(unsigned, b); }
; __device__ __forceinline__ float silu_f(float g) { return g * __builtin_amdgcn_rcpf(1.0f + __builtin_amdgcn_exp2f(-1.44269504f * g)); }
;     __device__ __forceinline__ void operator()(const f32x4 (&acc)[2][2][4][2], const Unit& u, int wr, int wc, int fr, int fq) const {
;         const int row0 = u.pm * BM + wr * 64 + fr, col0 = u.pn * HALF + wc * 32 + 8 * fq;
; #pragma unroll
;         for (int ai = 0; ai < 2; ++ai)
; #pragma unroll
;             for (int m = 0; m < 4; ++m) {
;                 const int row = row0 + ai * HALF + m * 16;
;                 const float rs = rowss ? __builtin_amdgcn_rsqf(rowss[row] * (1.0f / 1024.0f) + 1e-6f) : 1.0f;
;                 bf16_t* rowp = O + (size_t)row * ldc + col0;
;                 const f32x4 g0 = acc[ai][0][m][0] * rs, g1 = acc[ai][0][m][1] * rs, u0 = acc[ai][1][m][0] * rs, u1 = acc[ai][1][m][1] * rs;
;                 u32x4 w;
;                 w.x = cvt_pk_bf16(silu_f(g0[0]) * u0[0], silu_f(g0[1]) * u0[1]); w.y = cvt_pk_bf16(silu_f(g0[2]) * u0[2], silu_f(g0[3]) * u0[3]);
;                 w.z = cvt_pk_bf16(silu_f(g1[0]) * u1[0], silu_f(g1[1]) * u1[1]); w.w = cvt_pk_bf16(silu_f(g1[2]) * u1[2], silu_f(g1[3]) * u1[3]);
;                 *(u32x4*)rowp = w;
.LBB0_1106:
	v_lshl_add_u32 v144, s20, 8, v152
	v_ashrrev_i32_e32 v145, 31, v144
	v_lshl_add_u64 v[150:151], v[144:145], 2, s[0:1]
	v_or_b32_e32 v162, 16, v144
	v_ashrrev_i32_e32 v163, 31, v162
	v_lshl_add_u64 v[166:167], v[162:163], 2, s[0:1]
	v_lshl_or_b32 v148, s48, 7, v154
	v_mov_b64_e32 v[146:147], s[6:7]
	v_ashrrev_i32_e32 v149, 31, v148
	v_mad_i64_i32 v[160:161], s[22:23], v144, s47, v[146:147]
	v_lshlrev_b64 v[148:149], 1, v[148:149]
	v_lshl_add_u64 v[160:161], v[160:161], 0, v[148:149]
	s_andn2_b64 vcc, exec, s[2:3]
	s_mov_b64 s[2:3], -1
	v_fmamk_f32 v145, v237, 0x3a800000, v158
	v_rsq_f32_e32 v164, v145
	s_nop 0
	v_pk_mul_f32 v[126:127], v[126:127], v[164:165] op_sel_hi:[1,0]
	v_pk_mul_f32 v[124:125], v[124:125], v[164:165] op_sel_hi:[1,0]
	v_pk_mul_f32 v[122:123], v[122:123], v[164:165] op_sel_hi:[1,0]
	v_pk_mul_f32 v[120:121], v[120:121], v[164:165] op_sel_hi:[1,0]
	v_pk_mul_f32 v[118:119], v[118:119], v[164:165] op_sel_hi:[1,0]
	v_pk_mul_f32 v[116:117], v[116:117], v[164:165] op_sel_hi:[1,0]
	v_pk_mul_f32 v[114:115], v[114:115], v[164:165] op_sel_hi:[1,0]
	v_pk_mul_f32 v[112:113], v[112:113], v[164:165] op_sel_hi:[1,0]
	v_mul_f32_e32 v145, 0xbfb8aa3b, v124
	v_mul_f32_e32 v159, 0xbfb8aa3b, v125
	v_mul_f32_e32 v163, 0xbfb8aa3b, v126
	v_mul_f32_e32 v164, 0xbfb8aa3b, v127
	v_mul_f32_e32 v165, 0xbfb8aa3b, v120
	v_mul_f32_e32 v168, 0xbfb8aa3b, v121
	v_mul_f32_e32 v169, 0xbfb8aa3b, v122
	v_mul_f32_e32 v170, 0xbfb8aa3b, v123
	v_exp_f32_e32 v145, v145
	v_exp_f32_e32 v159, v159
	v_exp_f32_e32 v163, v163
	v_exp_f32_e32 v164, v164
	v_exp_f32_e32 v165, v165
	v_exp_f32_e32 v168, v168
	v_exp_f32_e32 v169, v169
	v_exp_f32_e32 v170, v170
	v_add_f32_e32 v145, 1.0, v145
	v_add_f32_e32 v159, 1.0, v159
	v_add_f32_e32 v163, 1.0, v163
	v_add_f32_e32 v171, 1.0, v164
	v_add_f32_e32 v172, 1.0, v165
	v_add_f32_e32 v173, 1.0, v168
	v_add_f32_e32 v174, 1.0, v169
	v_add_f32_e32 v175, 1.0, v170
	v_rcp_f32_e32 v164, v145
	v_rcp_f32_e32 v165, v159
	v_rcp_f32_e32 v168, v163
	v_rcp_f32_e32 v169, v171
	v_rcp_f32_e32 v170, v172
	v_rcp_f32_e32 v171, v173
	v_rcp_f32_e32 v172, v174
	v_rcp_f32_e32 v173, v175
	v_pk_mul_f32 v[124:125], v[124:125], v[164:165]
	v_pk_mul_f32 v[126:127], v[126:127], v[168:169]
	v_pk_mul_f32 v[120:121], v[120:121], v[170:171]
	v_pk_mul_f32 v[122:123], v[122:123], v[172:173]
	v_pk_mul_f32 v[116:117], v[116:117], v[124:125]
	v_pk_mul_f32 v[118:119], v[118:119], v[126:127]
	v_pk_mul_f32 v[120:121], v[112:113], v[120:121]
	v_pk_mul_f32 v[122:123], v[114:115], v[122:123]
	v_cvt_pk_bf16_f32 v112, v116, v117
	v_cvt_pk_bf16_f32 v113, v118, v119
	v_cvt_pk_bf16_f32 v114, v120, v121
	v_cvt_pk_bf16_f32 v115, v122, v123
	global_store_dwordx4 v[160:161], v[112:115], off
	s_nop 1
	s_nop 0
	v_or_b32_e32 v112, 32, v144
	v_mad_i64_i32 v[114:115], s[22:23], v162, s47, v[146:147]
	v_lshl_add_u64 v[114:115], v[114:115], 0, v[148:149]
	v_fmamk_f32 v113, v230, 0x3a800000, v158
	v_rsq_f32_e32 v116, v113
	v_ashrrev_i32_e32 v113, 31, v112
	v_lshl_add_u64 v[118:119], v[112:113], 2, s[0:1]
	v_pk_mul_f32 v[110:111], v[110:111], v[116:117] op_sel_hi:[1,0]
	v_pk_mul_f32 v[108:109], v[108:109], v[116:117] op_sel_hi:[1,0]
	v_pk_mul_f32 v[106:107], v[106:107], v[116:117] op_sel_hi:[1,0]
	v_pk_mul_f32 v[104:105], v[104:105], v[116:117] op_sel_hi:[1,0]
	v_pk_mul_f32 v[102:103], v[102:103], v[116:117] op_sel_hi:[1,0]
	v_pk_mul_f32 v[100:101], v[100:101], v[116:117] op_sel_hi:[1,0]
	v_pk_mul_f32 v[98:99], v[98:99], v[116:117] op_sel_hi:[1,0]
	v_pk_mul_f32 v[96:97], v[96:97], v[116:117] op_sel_hi:[1,0]
	v_mul_f32_e32 v113, 0xbfb8aa3b, v108
	v_mul_f32_e32 v116, 0xbfb8aa3b, v109
	v_mul_f32_e32 v117, 0xbfb8aa3b, v110
	v_mul_f32_e32 v120, 0xbfb8aa3b, v111
	v_mul_f32_e32 v121, 0xbfb8aa3b, v104
	v_mul_f32_e32 v122, 0xbfb8aa3b, v105
	v_mul_f32_e32 v123, 0xbfb8aa3b, v106
	v_mul_f32_e32 v124, 0xbfb8aa3b, v107
	v_exp_f32_e32 v113, v113
	v_exp_f32_e32 v116, v116
	v_exp_f32_e32 v117, v117
	v_exp_f32_e32 v120, v120
	v_exp_f32_e32 v121, v121
	v_exp_f32_e32 v122, v122
	v_exp_f32_e32 v123, v123
	v_exp_f32_e32 v124, v124
	v_add_f32_e32 v113, 1.0, v113
	v_add_f32_e32 v125, 1.0, v116
	v_add_f32_e32 v126, 1.0, v117
	v_add_f32_e32 v127, 1.0, v120
	v_add_f32_e32 v145, 1.0, v121
	v_add_f32_e32 v159, 1.0, v122
	v_add_f32_e32 v160, 1.0, v123
	v_add_f32_e32 v161, 1.0, v124
	v_rcp_f32_e32 v116, v113
	v_rcp_f32_e32 v117, v125
	v_rcp_f32_e32 v120, v126
	v_rcp_f32_e32 v121, v127
	v_rcp_f32_e32 v122, v145
	v_rcp_f32_e32 v123, v159
	v_rcp_f32_e32 v124, v160
	v_rcp_f32_e32 v125, v161
	v_pk_mul_f32 v[108:109], v[108:109], v[116:117]
	v_pk_mul_f32 v[110:111], v[110:111], v[120:121]
	v_pk_mul_f32 v[104:105], v[104:105], v[122:123]
	v_pk_mul_f32 v[106:107], v[106:107], v[124:125]
	v_pk_mul_f32 v[100:101], v[100:101], v[108:109]
	v_pk_mul_f32 v[102:103], v[102:103], v[110:111]
	v_pk_mul_f32 v[104:105], v[96:97], v[104:105]
	v_pk_mul_f32 v[106:107], v[98:99], v[106:107]
	v_cvt_pk_bf16_f32 v96, v100, v101
	v_cvt_pk_bf16_f32 v97, v102, v103
	v_cvt_pk_bf16_f32 v98, v104, v105
	v_cvt_pk_bf16_f32 v99, v106, v107
	global_store_dwordx4 v[114:115], v[96:99], off
	s_nop 1
	s_nop 0
	v_or_b32_e32 v96, 48, v144
	v_mad_i64_i32 v[98:99], s[22:23], v112, s47, v[146:147]
	v_lshl_add_u64 v[98:99], v[98:99], 0, v[148:149]
	v_fmamk_f32 v97, v231, 0x3a800000, v158
	v_rsq_f32_e32 v100, v97
	v_ashrrev_i32_e32 v97, 31, v96
	v_lshl_add_u64 v[102:103], v[96:97], 2, s[0:1]
	v_pk_mul_f32 v[94:95], v[94:95], v[100:101] op_sel_hi:[1,0]
	v_pk_mul_f32 v[92:93], v[92:93], v[100:101] op_sel_hi:[1,0]
	v_pk_mul_f32 v[90:91], v[90:91], v[100:101] op_sel_hi:[1,0]
	v_pk_mul_f32 v[88:89], v[88:89], v[100:101] op_sel_hi:[1,0]
; __device__ __forceinline__ unsigned cvt_pk_bf16(float lo, float hi) { f32x2_t v = {lo, hi}; bf16x2_t b = __builtin_convertvector(v, bf16x2_t); return __builtin_bit_cast(unsigned, b); }
; __device__ __forceinline__ float silu_f(float g) { return g * __builtin_amdgcn_rcpf(1.0f + __builtin_amdgcn_exp2f(-1.44269504f * g)); }
;     __device__ __forceinline__ void operator()(const f32x4 (&acc)[2][2][4][2], const Unit& u, int wr, int wc, int fr, int fq) const {
;         const int row0 = u.pm * BM + wr * 64 + fr, col0 = u.pn * HALF + wc * 32 + 8 * fq;
; #pragma unroll
;         for (int ai = 0; ai < 2; ++ai)
; #pragma unroll
;             for (int m = 0; m < 4; ++m) {
;                 const int row = row0 + ai * HALF + m * 16;
;                 const float rs = rowss ? __builtin_amdgcn_rsqf(rowss[row] * (1.0f / 1024.0f) + 1e-6f) : 1.0f;
;                 bf16_t* rowp = O + (size_t)row * ldc + col0;
;                 const f32x4 g0 = acc[ai][0][m][0] * rs, g1 = acc[ai][0][m][1] * rs, u0 = acc[ai][1][m][0] * rs, u1 = acc[ai][1][m][1] * rs;
;                 u32x4 w;
;                 w.x = cvt_pk_bf16(silu_f(g0[0]) * u0[0], silu_f(g0[1]) * u0[1]); w.y = cvt_pk_bf16(silu_f(g0[2]) * u0[2], silu_f(g0[3]) * u0[3]);
;                 w.z = cvt_pk_bf16(silu_f(g1[0]) * u1[0], silu_f(g1[1]) * u1[1]); w.w = cvt_pk_bf16(silu_f(g1[2]) * u1[2], silu_f(g1[3]) * u1[3]);
;                 *(u32x4*)rowp = w;
	v_pk_mul_f32 v[86:87], v[86:87], v[100:101] op_sel_hi:[1,0]
	v_pk_mul_f32 v[84:85], v[84:85], v[100:101] op_sel_hi:[1,0]
	v_pk_mul_f32 v[82:83], v[82:83], v[100:101] op_sel_hi:[1,0]
	v_pk_mul_f32 v[80:81], v[80:81], v[100:101] op_sel_hi:[1,0]
	v_mul_f32_e32 v97, 0xbfb8aa3b, v92
	v_mul_f32_e32 v100, 0xbfb8aa3b, v93
	v_mul_f32_e32 v101, 0xbfb8aa3b, v94
	v_mul_f32_e32 v104, 0xbfb8aa3b, v95
	v_mul_f32_e32 v105, 0xbfb8aa3b, v88
	v_mul_f32_e32 v106, 0xbfb8aa3b, v89
	v_mul_f32_e32 v107, 0xbfb8aa3b, v90
	v_mul_f32_e32 v108, 0xbfb8aa3b, v91
	v_exp_f32_e32 v97, v97
	v_exp_f32_e32 v100, v100
	v_exp_f32_e32 v101, v101
	v_exp_f32_e32 v104, v104
	v_exp_f32_e32 v105, v105
	v_exp_f32_e32 v106, v106
	v_exp_f32_e32 v107, v107
	v_exp_f32_e32 v108, v108
	v_add_f32_e32 v97, 1.0, v97
	v_add_f32_e32 v109, 1.0, v100
	v_add_f32_e32 v110, 1.0, v101
	v_add_f32_e32 v111, 1.0, v104
	v_add_f32_e32 v112, 1.0, v105
	v_add_f32_e32 v113, 1.0, v106
	v_add_f32_e32 v114, 1.0, v107
	v_add_f32_e32 v115, 1.0, v108
	v_rcp_f32_e32 v100, v97
	v_rcp_f32_e32 v101, v109
	v_rcp_f32_e32 v104, v110
	v_rcp_f32_e32 v105, v111
	v_rcp_f32_e32 v106, v112
	v_rcp_f32_e32 v107, v113
	v_rcp_f32_e32 v108, v114
	v_rcp_f32_e32 v109, v115
	v_pk_mul_f32 v[92:93], v[92:93], v[100:101]
	v_pk_mul_f32 v[94:95], v[94:95], v[104:105]
	v_pk_mul_f32 v[88:89], v[88:89], v[106:107]
	v_pk_mul_f32 v[90:91], v[90:91], v[108:109]
	v_pk_mul_f32 v[84:85], v[84:85], v[92:93]
	v_pk_mul_f32 v[86:87], v[86:87], v[94:95]
	v_pk_mul_f32 v[88:89], v[80:81], v[88:89]
	v_pk_mul_f32 v[90:91], v[82:83], v[90:91]
	v_cvt_pk_bf16_f32 v80, v84, v85
	v_cvt_pk_bf16_f32 v81, v86, v87
	v_cvt_pk_bf16_f32 v82, v88, v89
	v_cvt_pk_bf16_f32 v83, v90, v91
	global_store_dwordx4 v[98:99], v[80:83], off
	s_nop 1
	s_nop 0
	v_mad_i64_i32 v[82:83], s[22:23], v96, s47, v[146:147]
	v_lshl_add_u64 v[82:83], v[82:83], 0, v[148:149]
	v_fmamk_f32 v80, v232, 0x3a800000, v158
	v_rsq_f32_e32 v80, v80
	s_nop 0
	v_pk_mul_f32 v[78:79], v[78:79], v[80:81] op_sel_hi:[1,0]
	v_pk_mul_f32 v[76:77], v[76:77], v[80:81] op_sel_hi:[1,0]
	v_pk_mul_f32 v[74:75], v[74:75], v[80:81] op_sel_hi:[1,0]
	v_pk_mul_f32 v[72:73], v[72:73], v[80:81] op_sel_hi:[1,0]
	v_pk_mul_f32 v[70:71], v[70:71], v[80:81] op_sel_hi:[1,0]
	v_pk_mul_f32 v[68:69], v[68:69], v[80:81] op_sel_hi:[1,0]
	v_pk_mul_f32 v[66:67], v[66:67], v[80:81] op_sel_hi:[1,0]
	v_pk_mul_f32 v[64:65], v[64:65], v[80:81] op_sel_hi:[1,0]
	v_mul_f32_e32 v80, 0xbfb8aa3b, v76
	v_mul_f32_e32 v81, 0xbfb8aa3b, v77
	v_mul_f32_e32 v84, 0xbfb8aa3b, v78
	v_mul_f32_e32 v85, 0xbfb8aa3b, v79
	v_mul_f32_e32 v86, 0xbfb8aa3b, v72
	v_mul_f32_e32 v87, 0xbfb8aa3b, v73
	v_mul_f32_e32 v88, 0xbfb8aa3b, v74
	v_mul_f32_e32 v89, 0xbfb8aa3b, v75
	v_exp_f32_e32 v80, v80
	v_exp_f32_e32 v81, v81
	v_exp_f32_e32 v84, v84
	v_exp_f32_e32 v85, v85
	v_exp_f32_e32 v86, v86
	v_exp_f32_e32 v87, v87
	v_exp_f32_e32 v88, v88
	v_exp_f32_e32 v89, v89
	v_add_f32_e32 v80, 1.0, v80
	v_add_f32_e32 v81, 1.0, v81
	v_add_f32_e32 v84, 1.0, v84
	v_add_f32_e32 v85, 1.0, v85
	v_add_f32_e32 v86, 1.0, v86
	v_add_f32_e32 v87, 1.0, v87
	v_add_f32_e32 v88, 1.0, v88
	v_add_f32_e32 v89, 1.0, v89
	v_rcp_f32_e32 v80, v80
	v_rcp_f32_e32 v81, v81
	v_rcp_f32_e32 v84, v84
	v_rcp_f32_e32 v85, v85
	v_rcp_f32_e32 v86, v86
	v_rcp_f32_e32 v87, v87
	v_rcp_f32_e32 v88, v88
	v_rcp_f32_e32 v89, v89
	v_pk_mul_f32 v[76:77], v[76:77], v[80:81]
	v_pk_mul_f32 v[78:79], v[78:79], v[84:85]
	v_pk_mul_f32 v[72:73], v[72:73], v[86:87]
	v_pk_mul_f32 v[74:75], v[74:75], v[88:89]
	v_pk_mul_f32 v[68:69], v[68:69], v[76:77]
	v_pk_mul_f32 v[70:71], v[70:71], v[78:79]
	v_pk_mul_f32 v[72:73], v[64:65], v[72:73]
	v_pk_mul_f32 v[74:75], v[66:67], v[74:75]
	v_cvt_pk_bf16_f32 v64, v68, v69
	v_cvt_pk_bf16_f32 v65, v70, v71
	v_cvt_pk_bf16_f32 v66, v72, v73
	v_cvt_pk_bf16_f32 v67, v74, v75
	global_store_dwordx4 v[82:83], v[64:67], off
	s_nop 1
	s_nop 0
	v_add_u32_e32 v65, 0x80, v144
	v_mad_i64_i32 v[66:67], s[22:23], v65, s47, v[146:147]
	v_lshl_add_u64 v[66:67], v[66:67], 0, v[148:149]
	v_fmamk_f32 v64, v233, 0x3a800000, v158
	v_rsq_f32_e32 v64, v64
	s_nop 0
	v_pk_mul_f32 v[62:63], v[62:63], v[64:65] op_sel_hi:[1,0]
	v_pk_mul_f32 v[60:61], v[60:61], v[64:65] op_sel_hi:[1,0]
	v_pk_mul_f32 v[58:59], v[58:59], v[64:65] op_sel_hi:[1,0]
	v_pk_mul_f32 v[56:57], v[56:57], v[64:65] op_sel_hi:[1,0]
	v_pk_mul_f32 v[54:55], v[54:55], v[64:65] op_sel_hi:[1,0]
	v_pk_mul_f32 v[52:53], v[52:53], v[64:65] op_sel_hi:[1,0]
	v_pk_mul_f32 v[50:51], v[50:51], v[64:65] op_sel_hi:[1,0]
	v_pk_mul_f32 v[48:49], v[48:49], v[64:65] op_sel_hi:[1,0]
	v_mul_f32_e32 v64, 0xbfb8aa3b, v60
	v_mul_f32_e32 v65, 0xbfb8aa3b, v61
	v_mul_f32_e32 v68, 0xbfb8aa3b, v62
	v_mul_f32_e32 v69, 0xbfb8aa3b, v63
	v_mul_f32_e32 v70, 0xbfb8aa3b, v56
	v_mul_f32_e32 v71, 0xbfb8aa3b, v57
	v_mul_f32_e32 v72, 0xbfb8aa3b, v58
	v_mul_f32_e32 v73, 0xbfb8aa3b, v59
	v_exp_f32_e32 v64, v64
	v_exp_f32_e32 v65, v65
	v_exp_f32_e32 v68, v68
	v_exp_f32_e32 v69, v69
	v_exp_f32_e32 v70, v70
	v_exp_f32_e32 v71, v71
	v_exp_f32_e32 v72, v72
	v_exp_f32_e32 v73, v73
	v_add_f32_e32 v64, 1.0, v64
	v_add_f32_e32 v65, 1.0, v65
	v_add_f32_e32 v68, 1.0, v68
	v_add_f32_e32 v69, 1.0, v69
	v_add_f32_e32 v70, 1.0, v70
	v_add_f32_e32 v71, 1.0, v71
	v_add_f32_e32 v72, 1.0, v72
	v_add_f32_e32 v73, 1.0, v73
	v_rcp_f32_e32 v64, v64
	v_rcp_f32_e32 v65, v65
	v_rcp_f32_e32 v68, v68
	v_rcp_f32_e32 v69, v69
	v_rcp_f32_e32 v70, v70
	v_rcp_f32_e32 v71, v71
	v_rcp_f32_e32 v72, v72
	v_rcp_f32_e32 v73, v73
	v_pk_mul_f32 v[60:61], v[60:61], v[64:65]
	v_pk_mul_f32 v[62:63], v[62:63], v[68:69]
	v_pk_mul_f32 v[56:57], v[56:57], v[70:71]
	v_pk_mul_f32 v[58:59], v[58:59], v[72:73]
	v_pk_mul_f32 v[52:53], v[52:53], v[60:61]
; __device__ __forceinline__ unsigned cvt_pk_bf16(float lo, float hi) { f32x2_t v = {lo, hi}; bf16x2_t b = __builtin_convertvector(v, bf16x2_t); return __builtin_bit_cast(unsigned, b); }
; __device__ __forceinline__ float silu_f(float g) { return g * __builtin_amdgcn_rcpf(1.0f + __builtin_amdgcn_exp2f(-1.44269504f * g)); }
; #define PG8_BAR __builtin_amdgcn_s_barrier()
;     __device__ __forceinline__ void operator()(const f32x4 (&acc)[2][2][4][2], const Unit& u, int wr, int wc, int fr, int fq) const {
;         const int row0 = u.pm * BM + wr * 64 + fr, col0 = u.pn * HALF + wc * 32 + 8 * fq;
; #pragma unroll
;         for (int ai = 0; ai < 2; ++ai)
; #pragma unroll
;             for (int m = 0; m < 4; ++m) {
;                 const int row = row0 + ai * HALF + m * 16;
;                 const float rs = rowss ? __builtin_amdgcn_rsqf(rowss[row] * (1.0f / 1024.0f) + 1e-6f) : 1.0f;
;                 bf16_t* rowp = O + (size_t)row * ldc + col0;
;                 const f32x4 g0 = acc[ai][0][m][0] * rs, g1 = acc[ai][0][m][1] * rs, u0 = acc[ai][1][m][0] * rs, u1 = acc[ai][1][m][1] * rs;
;                 u32x4 w;
;                 w.x = cvt_pk_bf16(silu_f(g0[0]) * u0[0], silu_f(g0[1]) * u0[1]); w.y = cvt_pk_bf16(silu_f(g0[2]) * u0[2], silu_f(g0[3]) * u0[3]);
;                 w.z = cvt_pk_bf16(silu_f(g1[0]) * u1[0], silu_f(g1[1]) * u1[1]); w.w = cvt_pk_bf16(silu_f(g1[2]) * u1[2], silu_f(g1[3]) * u1[3]);
;                 *(u32x4*)rowp = w;
; template <class Epi, class Sched, bool ALIGN_EPI = false, bool SP2 = false>
; __device__ __forceinline__ void gemm_phase(PG8_LAS unsigned char* lds, const Gemm g, const Sched& S, const Epi& E) {
;     ...
;         if (!has_next) break;
; #pragma unroll
;         for (int a = 0; a < 2; ++a)
; #pragma unroll
;             for (int b = 0; b < 2; ++b)
; #pragma unroll
;                 for (int m = 0; m < 4; ++m)
; #pragma unroll
;                     for (int n = 0; n < 2; ++n) acc[a][b][m][n] = (f32x4){0.f, 0.f, 0.f, 0.f};
;         cur = nxt; cA = nA; cB = nB; ++ui;
;         if constexpr (ALIGN_EPI) { if (wr == 1) PG8_BAR; }
	v_pk_mul_f32 v[54:55], v[54:55], v[62:63]
	v_pk_mul_f32 v[56:57], v[48:49], v[56:57]
	v_pk_mul_f32 v[58:59], v[50:51], v[58:59]
	v_cvt_pk_bf16_f32 v48, v52, v53
	v_cvt_pk_bf16_f32 v49, v54, v55
	v_cvt_pk_bf16_f32 v50, v56, v57
	v_cvt_pk_bf16_f32 v51, v58, v59
	global_store_dwordx4 v[66:67], v[48:51], off
	s_nop 1
	s_nop 0
	v_add_u32_e32 v49, 0x90, v144
	v_mad_i64_i32 v[50:51], s[22:23], v49, s47, v[146:147]
	v_lshl_add_u64 v[50:51], v[50:51], 0, v[148:149]
	v_fmamk_f32 v48, v234, 0x3a800000, v158
	v_rsq_f32_e32 v48, v48
	s_nop 0
	v_pk_mul_f32 v[46:47], v[46:47], v[48:49] op_sel_hi:[1,0]
	v_pk_mul_f32 v[44:45], v[44:45], v[48:49] op_sel_hi:[1,0]
	v_pk_mul_f32 v[42:43], v[42:43], v[48:49] op_sel_hi:[1,0]
	v_pk_mul_f32 v[40:41], v[40:41], v[48:49] op_sel_hi:[1,0]
	v_pk_mul_f32 v[38:39], v[38:39], v[48:49] op_sel_hi:[1,0]
	v_pk_mul_f32 v[36:37], v[36:37], v[48:49] op_sel_hi:[1,0]
	v_pk_mul_f32 v[34:35], v[34:35], v[48:49] op_sel_hi:[1,0]
	v_pk_mul_f32 v[32:33], v[32:33], v[48:49] op_sel_hi:[1,0]
	v_mul_f32_e32 v48, 0xbfb8aa3b, v44
	v_mul_f32_e32 v49, 0xbfb8aa3b, v45
	v_mul_f32_e32 v52, 0xbfb8aa3b, v46
	v_mul_f32_e32 v53, 0xbfb8aa3b, v47
	v_mul_f32_e32 v54, 0xbfb8aa3b, v40
	v_mul_f32_e32 v55, 0xbfb8aa3b, v41
	v_mul_f32_e32 v56, 0xbfb8aa3b, v42
	v_mul_f32_e32 v57, 0xbfb8aa3b, v43
	v_exp_f32_e32 v48, v48
	v_exp_f32_e32 v49, v49
	v_exp_f32_e32 v52, v52
	v_exp_f32_e32 v53, v53
	v_exp_f32_e32 v54, v54
	v_exp_f32_e32 v55, v55
	v_exp_f32_e32 v56, v56
	v_exp_f32_e32 v57, v57
	v_add_f32_e32 v48, 1.0, v48
	v_add_f32_e32 v49, 1.0, v49
	v_add_f32_e32 v52, 1.0, v52
	v_add_f32_e32 v53, 1.0, v53
	v_add_f32_e32 v54, 1.0, v54
	v_add_f32_e32 v55, 1.0, v55
	v_add_f32_e32 v56, 1.0, v56
	v_add_f32_e32 v57, 1.0, v57
	v_rcp_f32_e32 v48, v48
	v_rcp_f32_e32 v49, v49
	v_rcp_f32_e32 v52, v52
	v_rcp_f32_e32 v53, v53
	v_rcp_f32_e32 v54, v54
	v_rcp_f32_e32 v55, v55
	v_rcp_f32_e32 v56, v56
	v_rcp_f32_e32 v57, v57
	v_pk_mul_f32 v[44:45], v[44:45], v[48:49]
	v_pk_mul_f32 v[46:47], v[46:47], v[52:53]
	v_pk_mul_f32 v[40:41], v[40:41], v[54:55]
	v_pk_mul_f32 v[42:43], v[42:43], v[56:57]
	v_pk_mul_f32 v[36:37], v[36:37], v[44:45]
	v_pk_mul_f32 v[38:39], v[38:39], v[46:47]
	v_pk_mul_f32 v[40:41], v[32:33], v[40:41]
	v_pk_mul_f32 v[42:43], v[34:35], v[42:43]
	v_cvt_pk_bf16_f32 v32, v36, v37
	v_cvt_pk_bf16_f32 v33, v38, v39
	v_cvt_pk_bf16_f32 v34, v40, v41
	v_cvt_pk_bf16_f32 v35, v42, v43
	global_store_dwordx4 v[50:51], v[32:35], off
	s_nop 1
	s_nop 0
	v_add_u32_e32 v33, 0xa0, v144
	v_mad_i64_i32 v[34:35], s[22:23], v33, s47, v[146:147]
	v_lshl_add_u64 v[34:35], v[34:35], 0, v[148:149]
	v_fmamk_f32 v32, v235, 0x3a800000, v158
	v_rsq_f32_e32 v32, v32
	s_nop 0
	v_pk_mul_f32 v[30:31], v[30:31], v[32:33] op_sel_hi:[1,0]
	v_pk_mul_f32 v[28:29], v[28:29], v[32:33] op_sel_hi:[1,0]
	v_pk_mul_f32 v[26:27], v[26:27], v[32:33] op_sel_hi:[1,0]
	v_pk_mul_f32 v[24:25], v[24:25], v[32:33] op_sel_hi:[1,0]
	v_pk_mul_f32 v[22:23], v[22:23], v[32:33] op_sel_hi:[1,0]
	v_pk_mul_f32 v[20:21], v[20:21], v[32:33] op_sel_hi:[1,0]
	v_pk_mul_f32 v[18:19], v[18:19], v[32:33] op_sel_hi:[1,0]
	v_pk_mul_f32 v[16:17], v[16:17], v[32:33] op_sel_hi:[1,0]
	v_mul_f32_e32 v32, 0xbfb8aa3b, v28
	v_mul_f32_e32 v33, 0xbfb8aa3b, v29
	v_mul_f32_e32 v36, 0xbfb8aa3b, v30
	v_mul_f32_e32 v37, 0xbfb8aa3b, v31
	v_mul_f32_e32 v38, 0xbfb8aa3b, v24
	v_mul_f32_e32 v39, 0xbfb8aa3b, v25
	v_mul_f32_e32 v40, 0xbfb8aa3b, v26
	v_mul_f32_e32 v41, 0xbfb8aa3b, v27
	v_exp_f32_e32 v32, v32
	v_exp_f32_e32 v33, v33
	v_exp_f32_e32 v36, v36
	v_exp_f32_e32 v37, v37
	v_exp_f32_e32 v38, v38
	v_exp_f32_e32 v39, v39
	v_exp_f32_e32 v40, v40
	v_exp_f32_e32 v41, v41
	v_add_f32_e32 v32, 1.0, v32
	v_add_f32_e32 v33, 1.0, v33
	v_add_f32_e32 v36, 1.0, v36
	v_add_f32_e32 v37, 1.0, v37
	v_add_f32_e32 v38, 1.0, v38
	v_add_f32_e32 v39, 1.0, v39
	v_add_f32_e32 v40, 1.0, v40
	v_add_f32_e32 v41, 1.0, v41
	v_rcp_f32_e32 v32, v32
	v_rcp_f32_e32 v33, v33
	v_rcp_f32_e32 v36, v36
	v_rcp_f32_e32 v37, v37
	v_rcp_f32_e32 v38, v38
	v_rcp_f32_e32 v39, v39
	v_rcp_f32_e32 v40, v40
	v_rcp_f32_e32 v41, v41
	v_pk_mul_f32 v[28:29], v[28:29], v[32:33]
	v_pk_mul_f32 v[30:31], v[30:31], v[36:37]
	v_pk_mul_f32 v[24:25], v[24:25], v[38:39]
	v_pk_mul_f32 v[26:27], v[26:27], v[40:41]
	v_pk_mul_f32 v[20:21], v[20:21], v[28:29]
	v_pk_mul_f32 v[22:23], v[22:23], v[30:31]
	v_pk_mul_f32 v[24:25], v[16:17], v[24:25]
	v_pk_mul_f32 v[26:27], v[18:19], v[26:27]
	v_cvt_pk_bf16_f32 v16, v20, v21
	v_cvt_pk_bf16_f32 v17, v22, v23
	v_cvt_pk_bf16_f32 v18, v24, v25
	v_cvt_pk_bf16_f32 v19, v26, v27
	global_store_dwordx4 v[34:35], v[16:19], off
	s_nop 1
	s_nop 0
	v_add_u32_e32 v17, 0xb0, v144
	v_mad_i64_i32 v[18:19], s[22:23], v17, s47, v[146:147]
	v_lshl_add_u64 v[18:19], v[18:19], 0, v[148:149]
	v_fmamk_f32 v16, v236, 0x3a800000, v158
	v_rsq_f32_e32 v16, v16
	s_nop 0
	v_pk_mul_f32 v[14:15], v[14:15], v[16:17] op_sel_hi:[1,0]
	v_pk_mul_f32 v[12:13], v[12:13], v[16:17] op_sel_hi:[1,0]
	v_pk_mul_f32 v[10:11], v[10:11], v[16:17] op_sel_hi:[1,0]
	v_pk_mul_f32 v[8:9], v[8:9], v[16:17] op_sel_hi:[1,0]
	v_pk_mul_f32 v[6:7], v[6:7], v[16:17] op_sel_hi:[1,0]
	v_pk_mul_f32 v[4:5], v[4:5], v[16:17] op_sel_hi:[1,0]
	v_pk_mul_f32 v[2:3], v[2:3], v[16:17] op_sel_hi:[1,0]
	v_pk_mul_f32 v[0:1], v[0:1], v[16:17] op_sel_hi:[1,0]
	v_mul_f32_e32 v16, 0xbfb8aa3b, v12
	v_mul_f32_e32 v17, 0xbfb8aa3b, v13
	v_mul_f32_e32 v20, 0xbfb8aa3b, v14
	v_mul_f32_e32 v21, 0xbfb8aa3b, v15
	v_mul_f32_e32 v22, 0xbfb8aa3b, v8
	v_mul_f32_e32 v23, 0xbfb8aa3b, v9
	v_mul_f32_e32 v24, 0xbfb8aa3b, v10
	v_mul_f32_e32 v25, 0xbfb8aa3b, v11
	v_exp_f32_e32 v16, v16
	v_exp_f32_e32 v17, v17
	v_exp_f32_e32 v20, v20
	v_exp_f32_e32 v21, v21
	v_exp_f32_e32 v22, v22
	v_exp_f32_e32 v23, v23
	v_exp_f32_e32 v24, v24
	v_exp_f32_e32 v25, v25
	v_add_f32_e32 v16, 1.0, v16
	v_add_f32_e32 v17, 1.0, v17
	v_add_f32_e32 v20, 1.0, v20
	v_add_f32_e32 v21, 1.0, v21
	v_add_f32_e32 v22, 1.0, v22
	v_add_f32_e32 v23, 1.0, v23
	v_add_f32_e32 v24, 1.0, v24
	v_add_f32_e32 v25, 1.0, v25
	v_rcp_f32_e32 v16, v16
	v_rcp_f32_e32 v17, v17
	v_rcp_f32_e32 v20, v20
	v_rcp_f32_e32 v21, v21
	v_rcp_f32_e32 v22, v22
	v_rcp_f32_e32 v23, v23
	v_rcp_f32_e32 v24, v24
	v_rcp_f32_e32 v25, v25
	v_pk_mul_f32 v[12:13], v[12:13], v[16:17]
	v_pk_mul_f32 v[14:15], v[14:15], v[20:21]
	v_pk_mul_f32 v[8:9], v[8:9], v[22:23]
	v_pk_mul_f32 v[10:11], v[10:11], v[24:25]
	v_pk_mul_f32 v[4:5], v[4:5], v[12:13]
	v_pk_mul_f32 v[6:7], v[6:7], v[14:15]
	v_pk_mul_f32 v[8:9], v[0:1], v[8:9]
	v_pk_mul_f32 v[10:11], v[2:3], v[10:11]
	v_cvt_pk_bf16_f32 v0, v4, v5
	v_cvt_pk_bf16_f32 v1, v6, v7
	v_cvt_pk_bf16_f32 v2, v8, v9
	v_cvt_pk_bf16_f32 v3, v10, v11
	global_store_dwordx4 v[18:19], v[0:3], off
	s_cbranch_vccnz .LBB0_1099
	s_andn2_b64 vcc, exec, s[4:5]
	s_cbranch_vccnz .LBB0_1098
	s_barrier
	s_branch .LBB0_1098
